# baseline (speedup 1.0000x reference)
; template <int N, int K, int EPI>
; __device__ void gemm_phase(const u16* __restrict__ A, const u16* __restrict__ Bt, const EpiArgs ea, char* smem, int tid) {
;     ...
;     const int vn = v + gridDim.x;
;     const bool has_next = vn < nwg;
;     int pmn = pm, pnn = pn;
;     if (has_next) tile_map(vn, nN, pmn, pnn);
;     const u16* Abn = A + (size_t)pmn * BM * K;
;     const u16* Bbn = Bt + (size_t)pnn * BM * K;
; #pragma nounroll
;     for (int t = 0; t < nt; t += 2) {
;     ...
;     for (int ai = 0; ai < 2; ++ai)
; #pragma unroll
;       for (int bj = 0; bj < 2; ++bj)
; #pragma unroll
;         for (int m = 0; m < 4; ++m)
; #pragma unroll
;           for (int n = 0; n < 2; ++n) acc[ai][bj][m][n] = f32x4{0.f, 0.f, 0.f, 0.f};
.LBB0_63:
	s_ashr_i32 s3, s2, 31
	s_lshl_b64 s[8:9], s[2:3], 19
	s_add_u32 s8, s96, s8
	s_addc_u32 s9, s97, s9
	s_ashr_i32 s5, s4, 31
	s_lshl_b64 s[10:11], s[4:5], 19
	s_add_u32 s10, s22, s10
	v_mov_b32_e32 v0, 0
	s_addc_u32 s11, s23, s11
	s_mov_b32 s3, -2
	s_movk_i32 s5, 0x80
	s_mov_b64 s[16:17], s[12:13]
	v_mov_b32_e32 v1, v0
	v_pk_mov_b32 v[2:3], v[0:1], v[0:1] op_sel:[0,0]
	v_pk_mov_b32 v[4:5], v[0:1], v[0:1] op_sel:[0,0]
	v_pk_mov_b32 v[6:7], v[0:1], v[0:1] op_sel:[0,0]
	v_pk_mov_b32 v[8:9], v[0:1], v[0:1] op_sel:[0,0]
	v_pk_mov_b32 v[10:11], v[0:1], v[0:1] op_sel:[0,0]
	v_pk_mov_b32 v[12:13], v[0:1], v[0:1] op_sel:[0,0]
	v_pk_mov_b32 v[14:15], v[0:1], v[0:1] op_sel:[0,0]
	v_pk_mov_b32 v[16:17], v[0:1], v[0:1] op_sel:[0,0]
	v_pk_mov_b32 v[18:19], v[0:1], v[0:1] op_sel:[0,0]
	v_pk_mov_b32 v[20:21], v[0:1], v[0:1] op_sel:[0,0]
	v_pk_mov_b32 v[22:23], v[0:1], v[0:1] op_sel:[0,0]
	v_pk_mov_b32 v[24:25], v[0:1], v[0:1] op_sel:[0,0]
	v_pk_mov_b32 v[26:27], v[0:1], v[0:1] op_sel:[0,0]
	v_pk_mov_b32 v[28:29], v[0:1], v[0:1] op_sel:[0,0]
	v_pk_mov_b32 v[30:31], v[0:1], v[0:1] op_sel:[0,0]
	v_pk_mov_b32 v[32:33], v[0:1], v[0:1] op_sel:[0,0]
	v_pk_mov_b32 v[34:35], v[0:1], v[0:1] op_sel:[0,0]
	v_pk_mov_b32 v[36:37], v[0:1], v[0:1] op_sel:[0,0]
	v_pk_mov_b32 v[38:39], v[0:1], v[0:1] op_sel:[0,0]
	v_pk_mov_b32 v[40:41], v[0:1], v[0:1] op_sel:[0,0]
	v_pk_mov_b32 v[42:43], v[0:1], v[0:1] op_sel:[0,0]
	v_pk_mov_b32 v[44:45], v[0:1], v[0:1] op_sel:[0,0]
	v_pk_mov_b32 v[46:47], v[0:1], v[0:1] op_sel:[0,0]
	v_pk_mov_b32 v[48:49], v[0:1], v[0:1] op_sel:[0,0]
	v_pk_mov_b32 v[50:51], v[0:1], v[0:1] op_sel:[0,0]
	v_pk_mov_b32 v[52:53], v[0:1], v[0:1] op_sel:[0,0]
	v_pk_mov_b32 v[54:55], v[0:1], v[0:1] op_sel:[0,0]
	v_pk_mov_b32 v[56:57], v[0:1], v[0:1] op_sel:[0,0]
	v_pk_mov_b32 v[58:59], v[0:1], v[0:1] op_sel:[0,0]
	v_pk_mov_b32 v[60:61], v[0:1], v[0:1] op_sel:[0,0]
	v_pk_mov_b32 v[62:63], v[0:1], v[0:1] op_sel:[0,0]
	v_pk_mov_b32 v[64:65], v[0:1], v[0:1] op_sel:[0,0]
	v_pk_mov_b32 v[66:67], v[0:1], v[0:1] op_sel:[0,0]
	v_pk_mov_b32 v[68:69], v[0:1], v[0:1] op_sel:[0,0]
	v_pk_mov_b32 v[70:71], v[0:1], v[0:1] op_sel:[0,0]
	v_pk_mov_b32 v[72:73], v[0:1], v[0:1] op_sel:[0,0]
	v_pk_mov_b32 v[74:75], v[0:1], v[0:1] op_sel:[0,0]
	v_pk_mov_b32 v[76:77], v[0:1], v[0:1] op_sel:[0,0]
	v_pk_mov_b32 v[78:79], v[0:1], v[0:1] op_sel:[0,0]
	v_pk_mov_b32 v[80:81], v[0:1], v[0:1] op_sel:[0,0]
	v_pk_mov_b32 v[82:83], v[0:1], v[0:1] op_sel:[0,0]
	v_pk_mov_b32 v[84:85], v[0:1], v[0:1] op_sel:[0,0]
	v_pk_mov_b32 v[86:87], v[0:1], v[0:1] op_sel:[0,0]
	v_pk_mov_b32 v[88:89], v[0:1], v[0:1] op_sel:[0,0]
	v_pk_mov_b32 v[90:91], v[0:1], v[0:1] op_sel:[0,0]
	v_pk_mov_b32 v[92:93], v[0:1], v[0:1] op_sel:[0,0]
	v_pk_mov_b32 v[94:95], v[0:1], v[0:1] op_sel:[0,0]
	v_pk_mov_b32 v[96:97], v[0:1], v[0:1] op_sel:[0,0]
	v_pk_mov_b32 v[98:99], v[0:1], v[0:1] op_sel:[0,0]
	v_pk_mov_b32 v[100:101], v[0:1], v[0:1] op_sel:[0,0]
	v_pk_mov_b32 v[102:103], v[0:1], v[0:1] op_sel:[0,0]
	v_pk_mov_b32 v[104:105], v[0:1], v[0:1] op_sel:[0,0]
	v_pk_mov_b32 v[106:107], v[0:1], v[0:1] op_sel:[0,0]
	v_pk_mov_b32 v[108:109], v[0:1], v[0:1] op_sel:[0,0]
	v_pk_mov_b32 v[110:111], v[0:1], v[0:1] op_sel:[0,0]
	v_pk_mov_b32 v[112:113], v[0:1], v[0:1] op_sel:[0,0]
	v_pk_mov_b32 v[114:115], v[0:1], v[0:1] op_sel:[0,0]
	v_pk_mov_b32 v[116:117], v[0:1], v[0:1] op_sel:[0,0]
	v_pk_mov_b32 v[118:119], v[0:1], v[0:1] op_sel:[0,0]
	v_pk_mov_b32 v[120:121], v[0:1], v[0:1] op_sel:[0,0]
	v_pk_mov_b32 v[122:123], v[0:1], v[0:1] op_sel:[0,0]
	v_pk_mov_b32 v[124:125], v[0:1], v[0:1] op_sel:[0,0]
	v_pk_mov_b32 v[126:127], v[0:1], v[0:1] op_sel:[0,0]

; template <int N, int K, int EPI>
; __device__ void gemm_phase(const u16* __restrict__ A, const u16* __restrict__ Bt, const EpiArgs ea, char* smem, int tid) {
;     ...
;     const int vn = v + gridDim.x;
;     const bool has_next = vn < nwg;
;     int pmn = pm, pnn = pn;
;     if (has_next) tile_map(vn, nN, pmn, pnn);
;     const u16* Abn = A + (size_t)pmn * BM * K;
;     const u16* Bbn = Bt + (size_t)pnn * BM * K;
; #pragma nounroll
;     for (int t = 0; t < nt; t += 2) {
;     ...
;     for (int ai = 0; ai < 2; ++ai)
; #pragma unroll
;       for (int bj = 0; bj < 2; ++bj)
; #pragma unroll
;         for (int m = 0; m < 4; ++m)
; #pragma unroll
;           for (int n = 0; n < 2; ++n) acc[ai][bj][m][n] = f32x4{0.f, 0.f, 0.f, 0.f};
.LBB0_109:
	s_ashr_i32 s3, s2, 31
	s_lshl_b64 s[8:9], s[2:3], 19
	s_add_u32 s8, s40, s8
	s_addc_u32 s9, s41, s9
	s_ashr_i32 s7, s6, 31
	s_lshl_b64 s[10:11], s[6:7], 19
	s_add_u32 s10, s20, s10
	v_mov_b32_e32 v0, 0
	s_addc_u32 s11, s21, s11
	s_mov_b32 s3, -2
	s_movk_i32 s7, 0x80
	s_mov_b64 s[14:15], s[4:5]
	v_mov_b32_e32 v1, v0
	v_pk_mov_b32 v[2:3], v[0:1], v[0:1] op_sel:[0,0]
	v_pk_mov_b32 v[4:5], v[0:1], v[0:1] op_sel:[0,0]
	v_pk_mov_b32 v[6:7], v[0:1], v[0:1] op_sel:[0,0]
	v_pk_mov_b32 v[8:9], v[0:1], v[0:1] op_sel:[0,0]
	v_pk_mov_b32 v[10:11], v[0:1], v[0:1] op_sel:[0,0]
	v_pk_mov_b32 v[12:13], v[0:1], v[0:1] op_sel:[0,0]
	v_pk_mov_b32 v[14:15], v[0:1], v[0:1] op_sel:[0,0]
	v_pk_mov_b32 v[16:17], v[0:1], v[0:1] op_sel:[0,0]
	v_pk_mov_b32 v[18:19], v[0:1], v[0:1] op_sel:[0,0]
	v_pk_mov_b32 v[20:21], v[0:1], v[0:1] op_sel:[0,0]
	v_pk_mov_b32 v[22:23], v[0:1], v[0:1] op_sel:[0,0]
	v_pk_mov_b32 v[24:25], v[0:1], v[0:1] op_sel:[0,0]
	v_pk_mov_b32 v[26:27], v[0:1], v[0:1] op_sel:[0,0]
	v_pk_mov_b32 v[28:29], v[0:1], v[0:1] op_sel:[0,0]
	v_pk_mov_b32 v[30:31], v[0:1], v[0:1] op_sel:[0,0]
	v_pk_mov_b32 v[32:33], v[0:1], v[0:1] op_sel:[0,0]
	v_pk_mov_b32 v[34:35], v[0:1], v[0:1] op_sel:[0,0]
	v_pk_mov_b32 v[36:37], v[0:1], v[0:1] op_sel:[0,0]
	v_pk_mov_b32 v[38:39], v[0:1], v[0:1] op_sel:[0,0]
	v_pk_mov_b32 v[40:41], v[0:1], v[0:1] op_sel:[0,0]
	v_pk_mov_b32 v[42:43], v[0:1], v[0:1] op_sel:[0,0]
	v_pk_mov_b32 v[44:45], v[0:1], v[0:1] op_sel:[0,0]
	v_pk_mov_b32 v[46:47], v[0:1], v[0:1] op_sel:[0,0]
	v_pk_mov_b32 v[48:49], v[0:1], v[0:1] op_sel:[0,0]
	v_pk_mov_b32 v[50:51], v[0:1], v[0:1] op_sel:[0,0]
	v_pk_mov_b32 v[52:53], v[0:1], v[0:1] op_sel:[0,0]
	v_pk_mov_b32 v[54:55], v[0:1], v[0:1] op_sel:[0,0]
	v_pk_mov_b32 v[56:57], v[0:1], v[0:1] op_sel:[0,0]
	v_pk_mov_b32 v[58:59], v[0:1], v[0:1] op_sel:[0,0]
	v_pk_mov_b32 v[60:61], v[0:1], v[0:1] op_sel:[0,0]
	v_pk_mov_b32 v[62:63], v[0:1], v[0:1] op_sel:[0,0]
	v_pk_mov_b32 v[64:65], v[0:1], v[0:1] op_sel:[0,0]
	v_pk_mov_b32 v[66:67], v[0:1], v[0:1] op_sel:[0,0]
	v_pk_mov_b32 v[68:69], v[0:1], v[0:1] op_sel:[0,0]
	v_pk_mov_b32 v[70:71], v[0:1], v[0:1] op_sel:[0,0]
	v_pk_mov_b32 v[72:73], v[0:1], v[0:1] op_sel:[0,0]
	v_pk_mov_b32 v[74:75], v[0:1], v[0:1] op_sel:[0,0]
	v_pk_mov_b32 v[76:77], v[0:1], v[0:1] op_sel:[0,0]
	v_pk_mov_b32 v[78:79], v[0:1], v[0:1] op_sel:[0,0]
	v_pk_mov_b32 v[80:81], v[0:1], v[0:1] op_sel:[0,0]
	v_pk_mov_b32 v[82:83], v[0:1], v[0:1] op_sel:[0,0]
	v_pk_mov_b32 v[84:85], v[0:1], v[0:1] op_sel:[0,0]
	v_pk_mov_b32 v[86:87], v[0:1], v[0:1] op_sel:[0,0]
	v_pk_mov_b32 v[88:89], v[0:1], v[0:1] op_sel:[0,0]
	v_pk_mov_b32 v[90:91], v[0:1], v[0:1] op_sel:[0,0]
	v_pk_mov_b32 v[92:93], v[0:1], v[0:1] op_sel:[0,0]
	v_pk_mov_b32 v[94:95], v[0:1], v[0:1] op_sel:[0,0]
	v_pk_mov_b32 v[96:97], v[0:1], v[0:1] op_sel:[0,0]
	v_pk_mov_b32 v[98:99], v[0:1], v[0:1] op_sel:[0,0]
	v_pk_mov_b32 v[100:101], v[0:1], v[0:1] op_sel:[0,0]
	v_pk_mov_b32 v[102:103], v[0:1], v[0:1] op_sel:[0,0]
	v_pk_mov_b32 v[104:105], v[0:1], v[0:1] op_sel:[0,0]
	v_pk_mov_b32 v[106:107], v[0:1], v[0:1] op_sel:[0,0]
	v_pk_mov_b32 v[108:109], v[0:1], v[0:1] op_sel:[0,0]
	v_pk_mov_b32 v[110:111], v[0:1], v[0:1] op_sel:[0,0]
	v_pk_mov_b32 v[112:113], v[0:1], v[0:1] op_sel:[0,0]
	v_pk_mov_b32 v[114:115], v[0:1], v[0:1] op_sel:[0,0]
	v_pk_mov_b32 v[116:117], v[0:1], v[0:1] op_sel:[0,0]
	v_pk_mov_b32 v[118:119], v[0:1], v[0:1] op_sel:[0,0]
	v_pk_mov_b32 v[120:121], v[0:1], v[0:1] op_sel:[0,0]
	v_pk_mov_b32 v[122:123], v[0:1], v[0:1] op_sel:[0,0]
	v_pk_mov_b32 v[124:125], v[0:1], v[0:1] op_sel:[0,0]
	v_pk_mov_b32 v[126:127], v[0:1], v[0:1] op_sel:[0,0]

; template <int N, int K, int EPI>
; __device__ void gemm_phase(const u16* __restrict__ A, const u16* __restrict__ Bt, const EpiArgs ea, char* smem, int tid) {
;     ...
;     const int vn = v + gridDim.x;
;     const bool has_next = vn < nwg;
;     int pmn = pm, pnn = pn;
;     if (has_next) tile_map(vn, nN, pmn, pnn);
;     const u16* Abn = A + (size_t)pmn * BM * K;
;     const u16* Bbn = Bt + (size_t)pnn * BM * K;
; #pragma nounroll
;     for (int t = 0; t < nt; t += 2) {
;     ...
;     for (int ai = 0; ai < 2; ++ai)
; #pragma unroll
;       for (int bj = 0; bj < 2; ++bj)
; #pragma unroll
;         for (int m = 0; m < 4; ++m)
; #pragma unroll
;           for (int n = 0; n < 2; ++n) acc[ai][bj][m][n] = f32x4{0.f, 0.f, 0.f, 0.f};
.LBB0_219:
	s_mul_i32 s2, s67, 0x160000
	s_mul_hi_i32 s3, s67, 0x160000
	s_add_u32 s2, s80, s2
	s_addc_u32 s3, s81, s3
	s_mul_i32 s4, s72, 0x160000
	s_mul_hi_i32 s5, s72, 0x160000
	s_add_u32 s4, s16, s4
	v_mov_b32_e32 v0, 0
	s_addc_u32 s5, s17, s5
	s_mov_b32 s89, -2
	s_movk_i32 s94, 0x80
	s_mov_b64 s[10:11], s[6:7]
	v_mov_b32_e32 v1, v0
	v_pk_mov_b32 v[2:3], v[0:1], v[0:1] op_sel:[0,0]
	v_pk_mov_b32 v[4:5], v[0:1], v[0:1] op_sel:[0,0]
	v_pk_mov_b32 v[6:7], v[0:1], v[0:1] op_sel:[0,0]
	v_pk_mov_b32 v[8:9], v[0:1], v[0:1] op_sel:[0,0]
	v_pk_mov_b32 v[10:11], v[0:1], v[0:1] op_sel:[0,0]
	v_pk_mov_b32 v[12:13], v[0:1], v[0:1] op_sel:[0,0]
	v_pk_mov_b32 v[14:15], v[0:1], v[0:1] op_sel:[0,0]
	v_pk_mov_b32 v[16:17], v[0:1], v[0:1] op_sel:[0,0]
	v_pk_mov_b32 v[18:19], v[0:1], v[0:1] op_sel:[0,0]
	v_pk_mov_b32 v[20:21], v[0:1], v[0:1] op_sel:[0,0]
	v_pk_mov_b32 v[22:23], v[0:1], v[0:1] op_sel:[0,0]
	v_pk_mov_b32 v[24:25], v[0:1], v[0:1] op_sel:[0,0]
	v_pk_mov_b32 v[26:27], v[0:1], v[0:1] op_sel:[0,0]
	v_pk_mov_b32 v[28:29], v[0:1], v[0:1] op_sel:[0,0]
	v_pk_mov_b32 v[30:31], v[0:1], v[0:1] op_sel:[0,0]
	v_pk_mov_b32 v[32:33], v[0:1], v[0:1] op_sel:[0,0]
	v_pk_mov_b32 v[34:35], v[0:1], v[0:1] op_sel:[0,0]
	v_pk_mov_b32 v[36:37], v[0:1], v[0:1] op_sel:[0,0]
	v_pk_mov_b32 v[38:39], v[0:1], v[0:1] op_sel:[0,0]
	v_pk_mov_b32 v[40:41], v[0:1], v[0:1] op_sel:[0,0]
	v_pk_mov_b32 v[42:43], v[0:1], v[0:1] op_sel:[0,0]
	v_pk_mov_b32 v[44:45], v[0:1], v[0:1] op_sel:[0,0]
	v_pk_mov_b32 v[46:47], v[0:1], v[0:1] op_sel:[0,0]
	v_pk_mov_b32 v[48:49], v[0:1], v[0:1] op_sel:[0,0]
	v_pk_mov_b32 v[50:51], v[0:1], v[0:1] op_sel:[0,0]
	v_pk_mov_b32 v[52:53], v[0:1], v[0:1] op_sel:[0,0]
	v_pk_mov_b32 v[54:55], v[0:1], v[0:1] op_sel:[0,0]
	v_pk_mov_b32 v[56:57], v[0:1], v[0:1] op_sel:[0,0]
	v_pk_mov_b32 v[58:59], v[0:1], v[0:1] op_sel:[0,0]
	v_pk_mov_b32 v[60:61], v[0:1], v[0:1] op_sel:[0,0]
	v_pk_mov_b32 v[62:63], v[0:1], v[0:1] op_sel:[0,0]
	v_pk_mov_b32 v[64:65], v[0:1], v[0:1] op_sel:[0,0]
	v_pk_mov_b32 v[66:67], v[0:1], v[0:1] op_sel:[0,0]
	v_pk_mov_b32 v[68:69], v[0:1], v[0:1] op_sel:[0,0]
	v_pk_mov_b32 v[70:71], v[0:1], v[0:1] op_sel:[0,0]
	v_pk_mov_b32 v[72:73], v[0:1], v[0:1] op_sel:[0,0]
	v_pk_mov_b32 v[74:75], v[0:1], v[0:1] op_sel:[0,0]
	v_pk_mov_b32 v[76:77], v[0:1], v[0:1] op_sel:[0,0]
	v_pk_mov_b32 v[78:79], v[0:1], v[0:1] op_sel:[0,0]
	v_pk_mov_b32 v[80:81], v[0:1], v[0:1] op_sel:[0,0]
	v_pk_mov_b32 v[82:83], v[0:1], v[0:1] op_sel:[0,0]
	v_pk_mov_b32 v[84:85], v[0:1], v[0:1] op_sel:[0,0]
	v_pk_mov_b32 v[86:87], v[0:1], v[0:1] op_sel:[0,0]
	v_pk_mov_b32 v[88:89], v[0:1], v[0:1] op_sel:[0,0]
	v_pk_mov_b32 v[90:91], v[0:1], v[0:1] op_sel:[0,0]
	v_pk_mov_b32 v[92:93], v[0:1], v[0:1] op_sel:[0,0]
	v_pk_mov_b32 v[94:95], v[0:1], v[0:1] op_sel:[0,0]
	v_pk_mov_b32 v[96:97], v[0:1], v[0:1] op_sel:[0,0]
	v_pk_mov_b32 v[98:99], v[0:1], v[0:1] op_sel:[0,0]
	v_pk_mov_b32 v[100:101], v[0:1], v[0:1] op_sel:[0,0]
	v_pk_mov_b32 v[102:103], v[0:1], v[0:1] op_sel:[0,0]
	v_pk_mov_b32 v[104:105], v[0:1], v[0:1] op_sel:[0,0]
	v_pk_mov_b32 v[106:107], v[0:1], v[0:1] op_sel:[0,0]
	v_pk_mov_b32 v[108:109], v[0:1], v[0:1] op_sel:[0,0]
	v_pk_mov_b32 v[110:111], v[0:1], v[0:1] op_sel:[0,0]
	v_pk_mov_b32 v[112:113], v[0:1], v[0:1] op_sel:[0,0]
	v_pk_mov_b32 v[114:115], v[0:1], v[0:1] op_sel:[0,0]
	v_pk_mov_b32 v[116:117], v[0:1], v[0:1] op_sel:[0,0]
	v_pk_mov_b32 v[118:119], v[0:1], v[0:1] op_sel:[0,0]
	v_pk_mov_b32 v[120:121], v[0:1], v[0:1] op_sel:[0,0]
	v_pk_mov_b32 v[122:123], v[0:1], v[0:1] op_sel:[0,0]
	v_pk_mov_b32 v[124:125], v[0:1], v[0:1] op_sel:[0,0]
	v_pk_mov_b32 v[126:127], v[0:1], v[0:1] op_sel:[0,0]

; template <int N, int K, int EPI>
; __device__ void gemm_phase(const u16* __restrict__ A, const u16* __restrict__ Bt, const EpiArgs ea, char* smem, int tid) {
;     ...
;     const int vn = v + gridDim.x;
;     const bool has_next = vn < nwg;
;     int pmn = pm, pnn = pn;
;     if (has_next) tile_map(vn, nN, pmn, pnn);
;     const u16* Abn = A + (size_t)pmn * BM * K;
;     const u16* Bbn = Bt + (size_t)pnn * BM * K;
; #pragma nounroll
;     for (int t = 0; t < nt; t += 2) {
;     ...
;     for (int ai = 0; ai < 2; ++ai)
; #pragma unroll
;       for (int bj = 0; bj < 2; ++bj)
; #pragma unroll
;         for (int m = 0; m < 4; ++m)
; #pragma unroll
;           for (int n = 0; n < 2; ++n) acc[ai][bj][m][n] = f32x4{0.f, 0.f, 0.f, 0.f};
.LBB0_235:
	s_ashr_i32 s3, s2, 31
	s_lshl_b64 s[6:7], s[2:3], 19
	s_add_u32 s6, s40, s6
	s_addc_u32 s7, s41, s7
	s_ashr_i32 s5, s4, 31
	s_lshl_b64 s[8:9], s[4:5], 19
	s_add_u32 s8, s20, s8
	v_mov_b32_e32 v0, 0
	s_addc_u32 s9, s21, s9
	s_mov_b32 s3, -2
	s_movk_i32 s5, 0x80
	s_mov_b64 s[14:15], s[10:11]
	v_mov_b32_e32 v1, v0
	v_pk_mov_b32 v[2:3], v[0:1], v[0:1] op_sel:[0,0]
	v_pk_mov_b32 v[8:9], v[0:1], v[0:1] op_sel:[0,0]
	v_pk_mov_b32 v[10:11], v[0:1], v[0:1] op_sel:[0,0]
	v_pk_mov_b32 v[16:17], v[0:1], v[0:1] op_sel:[0,0]
	v_pk_mov_b32 v[18:19], v[0:1], v[0:1] op_sel:[0,0]
	v_pk_mov_b32 v[24:25], v[0:1], v[0:1] op_sel:[0,0]
	v_pk_mov_b32 v[26:27], v[0:1], v[0:1] op_sel:[0,0]
	v_pk_mov_b32 v[32:33], v[0:1], v[0:1] op_sel:[0,0]
	v_pk_mov_b32 v[34:35], v[0:1], v[0:1] op_sel:[0,0]
	v_pk_mov_b32 v[40:41], v[0:1], v[0:1] op_sel:[0,0]
	v_pk_mov_b32 v[42:43], v[0:1], v[0:1] op_sel:[0,0]
	v_pk_mov_b32 v[48:49], v[0:1], v[0:1] op_sel:[0,0]
	v_pk_mov_b32 v[50:51], v[0:1], v[0:1] op_sel:[0,0]
	v_pk_mov_b32 v[56:57], v[0:1], v[0:1] op_sel:[0,0]
	v_pk_mov_b32 v[58:59], v[0:1], v[0:1] op_sel:[0,0]
	v_pk_mov_b32 v[4:5], v[0:1], v[0:1] op_sel:[0,0]
	v_pk_mov_b32 v[6:7], v[0:1], v[0:1] op_sel:[0,0]
	v_pk_mov_b32 v[12:13], v[0:1], v[0:1] op_sel:[0,0]
	v_pk_mov_b32 v[14:15], v[0:1], v[0:1] op_sel:[0,0]
	v_pk_mov_b32 v[20:21], v[0:1], v[0:1] op_sel:[0,0]
	v_pk_mov_b32 v[22:23], v[0:1], v[0:1] op_sel:[0,0]
	v_pk_mov_b32 v[28:29], v[0:1], v[0:1] op_sel:[0,0]
	v_pk_mov_b32 v[30:31], v[0:1], v[0:1] op_sel:[0,0]
	v_pk_mov_b32 v[36:37], v[0:1], v[0:1] op_sel:[0,0]
	v_pk_mov_b32 v[38:39], v[0:1], v[0:1] op_sel:[0,0]
	v_pk_mov_b32 v[44:45], v[0:1], v[0:1] op_sel:[0,0]
	v_pk_mov_b32 v[46:47], v[0:1], v[0:1] op_sel:[0,0]
	v_pk_mov_b32 v[52:53], v[0:1], v[0:1] op_sel:[0,0]
	v_pk_mov_b32 v[54:55], v[0:1], v[0:1] op_sel:[0,0]
	v_pk_mov_b32 v[60:61], v[0:1], v[0:1] op_sel:[0,0]
	v_pk_mov_b32 v[62:63], v[0:1], v[0:1] op_sel:[0,0]
	v_pk_mov_b32 v[64:65], v[0:1], v[0:1] op_sel:[0,0]
	v_pk_mov_b32 v[66:67], v[0:1], v[0:1] op_sel:[0,0]
	v_pk_mov_b32 v[72:73], v[0:1], v[0:1] op_sel:[0,0]
	v_pk_mov_b32 v[74:75], v[0:1], v[0:1] op_sel:[0,0]
	v_pk_mov_b32 v[80:81], v[0:1], v[0:1] op_sel:[0,0]
	v_pk_mov_b32 v[82:83], v[0:1], v[0:1] op_sel:[0,0]
	v_pk_mov_b32 v[88:89], v[0:1], v[0:1] op_sel:[0,0]
	v_pk_mov_b32 v[90:91], v[0:1], v[0:1] op_sel:[0,0]
	v_pk_mov_b32 v[96:97], v[0:1], v[0:1] op_sel:[0,0]
	v_pk_mov_b32 v[98:99], v[0:1], v[0:1] op_sel:[0,0]
	v_pk_mov_b32 v[104:105], v[0:1], v[0:1] op_sel:[0,0]
	v_pk_mov_b32 v[106:107], v[0:1], v[0:1] op_sel:[0,0]
	v_pk_mov_b32 v[112:113], v[0:1], v[0:1] op_sel:[0,0]
	v_pk_mov_b32 v[114:115], v[0:1], v[0:1] op_sel:[0,0]
	v_pk_mov_b32 v[120:121], v[0:1], v[0:1] op_sel:[0,0]
	v_pk_mov_b32 v[122:123], v[0:1], v[0:1] op_sel:[0,0]
	v_pk_mov_b32 v[68:69], v[0:1], v[0:1] op_sel:[0,0]
	v_pk_mov_b32 v[70:71], v[0:1], v[0:1] op_sel:[0,0]
	v_pk_mov_b32 v[76:77], v[0:1], v[0:1] op_sel:[0,0]
	v_pk_mov_b32 v[78:79], v[0:1], v[0:1] op_sel:[0,0]
	v_pk_mov_b32 v[84:85], v[0:1], v[0:1] op_sel:[0,0]
	v_pk_mov_b32 v[86:87], v[0:1], v[0:1] op_sel:[0,0]
	v_pk_mov_b32 v[92:93], v[0:1], v[0:1] op_sel:[0,0]
	v_pk_mov_b32 v[94:95], v[0:1], v[0:1] op_sel:[0,0]
	v_pk_mov_b32 v[100:101], v[0:1], v[0:1] op_sel:[0,0]
	v_pk_mov_b32 v[102:103], v[0:1], v[0:1] op_sel:[0,0]
	v_pk_mov_b32 v[108:109], v[0:1], v[0:1] op_sel:[0,0]
	v_pk_mov_b32 v[110:111], v[0:1], v[0:1] op_sel:[0,0]
	v_pk_mov_b32 v[116:117], v[0:1], v[0:1] op_sel:[0,0]
	v_pk_mov_b32 v[118:119], v[0:1], v[0:1] op_sel:[0,0]
	v_pk_mov_b32 v[124:125], v[0:1], v[0:1] op_sel:[0,0]
	v_pk_mov_b32 v[126:127], v[0:1], v[0:1] op_sel:[0,0]
